# RWKV-7 chunk-record builder: next unit's nine token-operand loads issued into spare registers after step 1 (software pipelining across units)
# speedup vs baseline: 1.0081x; 1.0081x over previous
.LBB0_317:
	v_writelane_b32 v249, s0, 38
	s_and_b64 vcc, exec, s[2:3]
	s_nop 0
	v_writelane_b32 v249, s1, 39
	s_cbranch_vccz .LBB0_905
	s_cmp_eq_u32 s80, 4
	s_cselect_b64 s[0:1], -1, 0
	s_cmp_lg_u32 s80, 4
	s_cselect_b64 s[2:3], -1, 0
	v_writelane_b32 v249, s2, 40
	s_cmp_lt_u32 s8, 9
	s_cselect_b64 s[72:73], -1, 0
	v_writelane_b32 v249, s3, 41
	v_writelane_b32 v249, s0, 42
	s_mov_b64 s[46:47], 0x1000
	s_nop 0
	v_writelane_b32 v249, s1, 43
	s_and_b64 s[0:1], s[0:1], s[72:73]
	s_andn2_b64 vcc, exec, s[0:1]
	s_cbranch_vccnz .LBB0_486
	s_cmpk_gt_i32 s64, 0x8ff
	s_cbranch_scc1 .LBB0_342
	v_readlane_b32 s0, v249, 36
	s_lshl_b32 s8, s64, 2
	s_lshl_b32 s9, s0, 2
	s_mov_b32 s22, s64
	v_readlane_b32 s1, v249, 37
	s_mov_b32 s100, s8
	v_mbcnt_lo_u32_b32 v166, -1, 0
	v_mbcnt_hi_u32_b32 v166, -1, v166
	v_add_u32_e32 v167, s61, v166
	v_lshrrev_b32_e32 v168, 7, v167
	v_add_u32_e32 v168, s100, v168
	s_load_dwordx2 s[100:101], s[58:59], 0x158
	v_lshlrev_b32_e32 v169, 4, v168
	v_and_b32_e32 v169, 0x7f0, v169
	v_ashrrev_i32_e32 v170, 10, v168
	v_lshl_or_b32 v170, v170, 11, v169
	v_lshrrev_b32_e32 v171, 7, v168
	v_add_u32_e32 v172, 0xffffe000, v168
	v_and_b32_e32 v172, -8, v172
	v_add_u32_e32 v172, 0x4000, v172
	v_cmp_lt_i32_e32 vcc, 0x1fff, v168
	v_cndmask_b32_e32 v170, v170, v172, vcc
	v_cndmask_b32_e64 v169, v169, 0, vcc
	v_cndmask_b32_e32 v171, v171, v168, vcc
	v_mov_b32_e32 v173, 16
	v_cndmask_b32_e64 v173, v173, 8, vcc
	v_bfe_u32 v174, v167, 6, 1
	v_bfe_u32 v175, v166, 3, 3
	v_lshl_or_b32 v174, v174, 3, v175
	v_cmp_gt_u32_e32 vcc, v173, v174
	v_cndmask_b32_e32 v174, 0, v174, vcc
	v_lshlrev_b32_e32 v171, 6, v171
	v_and_b32_e32 v171, 0x1c0, v171
	v_lshlrev_b32_e32 v175, 3, v167
	v_and_b32_e32 v175, 56, v175
	v_or_b32_e32 v171, v171, v175
	v_add_u32_e32 v170, v170, v174
	v_or_b32_e32 v169, v169, v174
	v_lshlrev_b32_e32 v176, 1, v171
	v_mov_b32_e32 v177, 0
	v_mov_b32_e32 v178, 0xc00
	s_waitcnt lgkmcnt(0)
	v_mov_b64_e32 v[180:181], s[100:101]
	v_mov_b64_e32 v[182:183], s[100:101]
	v_mad_i64_i32 v[180:181], vcc, v170, s83, v[180:181]
	v_mad_i64_i32 v[182:183], vcc, v170, v178, v[182:183]
	v_lshl_add_u64 v[180:181], v[180:181], 0, v[176:177]
	v_lshl_add_u64 v[182:183], v[182:183], 0, v[176:177]
	v_add_co_u32_e32 v180, vcc, 0x12f01000, v180
	v_addc_co_u32_e32 v181, vcc, 0, v181, vcc
	v_add_co_u32_e32 v182, vcc, 0x25600000, v182
	v_addc_co_u32_e32 v183, vcc, 0, v183, vcc
	v_cmp_eq_u32_e32 vcc, 0, v169
	v_cndmask_b32_e64 v185, -1, 0, vcc
	v_cndmask_b32_e64 v184, v205, 0, vcc
	v_lshl_add_u64 v[184:185], v[180:181], 0, v[184:185]
	global_load_dwordx4 v[128:131], v[182:183], off
	global_load_dwordx4 v[132:135], v[184:185], off
	global_load_dwordx4 v[136:139], v[184:185], off offset:1024
	global_load_dwordx4 v[140:143], v[180:181], off offset:1024
	global_load_dwordx4 v[144:147], v[180:181], off offset:2048
	global_load_dwordx4 v[148:151], v[180:181], off
	global_load_dwordx4 v[152:155], v[184:185], off offset:2048
	global_load_dwordx4 v[158:161], v[182:183], off offset:1024
	global_load_dwordx4 v[162:165], v[182:183], off offset:2048
	s_branch .LBB0_322

.LBB0_326:
	s_bfe_u32 s23, s23, 0x10006
	v_bfe_u32 v0, v107, 3, 3
	v_lshl_or_b32 v109, s23, 3, v0
	s_lshl_b32 s14, s26, 6
	v_lshlrev_b32_e32 v106, 3, v108
	v_cmp_gt_u32_e32 vcc, s7, v109
	s_and_b32 s14, s14, 0x1c0
	v_and_b32_e32 v88, 56, v106
	v_cndmask_b32_e32 v0, 0, v109, vcc
	v_or_b32_e32 v14, s14, v88
	v_add_u32_e32 v6, s25, v0
	v_or_b32_e32 v8, s24, v0
	s_waitcnt lgkmcnt(0)
	v_mov_b64_e32 v[0:1], s[4:5]
	v_mad_i64_i32 v[0:1], s[4:5], v6, s83, v[0:1]
	v_lshlrev_b32_e32 v156, 1, v14
	v_lshl_add_u64 v[0:1], v[0:1], 0, v[156:157]
	s_mov_b64 s[4:5], 0x12f01000
	v_lshl_add_u64 v[2:3], v[0:1], 0, s[4:5]
	v_mov_b64_e32 v[4:5], s[2:3]
	s_movk_i32 s2, 0xc00
	s_mov_b32 s4, 0x12f01000
	v_mad_i64_i32 v[4:5], s[2:3], v6, s2, v[4:5]
	v_add_co_u32_e32 v0, vcc, s4, v0
	v_lshl_add_u64 v[4:5], v[4:5], 0, v[156:157]
	s_mov_b64 s[2:3], 0x25600000
	v_addc_co_u32_e32 v1, vcc, 0, v1, vcc
	s_mov_b32 s4, 0x25600000
	v_lshl_add_u64 v[6:7], v[4:5], 0, s[2:3]
	v_cmp_eq_u32_e64 s[2:3], 0, v8
	v_add_co_u32_e32 v4, vcc, s4, v4
	s_nop 0
	v_cndmask_b32_e64 v9, -1, 0, s[2:3]
	v_cndmask_b32_e64 v8, v205, 0, s[2:3]
	v_addc_co_u32_e32 v5, vcc, 0, v5, vcc
	v_lshl_add_u64 v[12:13], v[2:3], 0, v[8:9]
	s_load_dwordx2 s[4:5], s[18:19], 0xb0
	v_lshlrev_b32_e32 v156, 2, v14
	s_nop 0
	s_waitcnt lgkmcnt(0)
	global_load_dwordx4 v[52:55], v156, s[4:5] offset:16
	global_load_dwordx4 v[56:59], v156, s[4:5]
	global_load_dwordx4 v[40:43], v156, s[4:5] offset:2064
	global_load_dwordx4 v[48:51], v156, s[4:5] offset:2048
	v_lshl_add_u64 v[4:5], s[4:5], 0, v[156:157]
	v_lshl_add_u64 v[6:7], v[4:5], 0, s[46:47]
	v_add_co_u32_e32 v4, vcc, 0x1000, v4
	v_cmp_le_u32_e64 s[4:5], s7, v109
	s_nop 0
	v_addc_co_u32_e32 v5, vcc, 0, v5, vcc
	global_load_dwordx4 v[12:15], v[4:5], off
	s_nop 0
	global_load_dwordx4 v[4:7], v[6:7], off offset:16
	s_and_b64 s[14:15], s[12:13], s[2:3]
	v_mov_b32_e32 v60, 0
	v_mov_b32_e32 v61, 0
	v_mov_b32_e32 v62, 0
	v_mov_b32_e32 v63, 0
	v_mov_b32_e32 v64, 0
	v_mov_b32_e32 v65, 0
	v_mov_b32_e32 v66, 0
	v_mov_b32_e32 v67, 0
	v_mov_b32_e32 v68, 0
	v_mov_b32_e32 v69, 0
	v_mov_b32_e32 v70, 0
	v_mov_b32_e32 v71, 0
	v_mov_b32_e32 v44, 0
	v_mov_b32_e32 v45, 0
	v_mov_b32_e32 v46, 0
	v_mov_b32_e32 v47, 0
	v_mov_b32_e32 v20, 0
	v_mov_b32_e32 v21, 0
	v_mov_b32_e32 v22, 0
	v_mov_b32_e32 v23, 0
	v_mov_b32_e32 v16, 0
	v_mov_b32_e32 v17, 0
	v_mov_b32_e32 v18, 0
	v_mov_b32_e32 v19, 0
	s_and_saveexec_b64 s[12:13], s[14:15]
	s_cbranch_execz .LBB0_328
	s_load_dwordx2 s[14:15], s[18:19], 0x30
	s_mul_hi_i32 s7, s1, 0x1c00
	s_mulk_i32 s1, 0x1c00
	s_waitcnt lgkmcnt(0)
	s_add_u32 s14, s14, s1
	s_addc_u32 s15, s15, s7
	v_lshl_add_u64 v[16:17], s[14:15], 0, v[156:157]
	global_load_dwordx4 v[60:63], v156, s[14:15]
	global_load_dwordx4 v[64:67], v156, s[14:15] offset:16
	global_load_dwordx4 v[68:71], v156, s[14:15] offset:2048
	global_load_dwordx4 v[44:47], v156, s[14:15] offset:2064
	v_lshl_add_u64 v[18:19], v[16:17], 0, s[46:47]
	v_add_co_u32_e32 v16, vcc, 0x1000, v16
	s_nop 1
	v_addc_co_u32_e32 v17, vcc, 0, v17, vcc
	global_load_dwordx4 v[20:23], v[16:17], off
	s_nop 0
	global_load_dwordx4 v[16:19], v[18:19], off offset:16
.LBB0_328:
	s_or_b64 exec, exec, s[12:13]
	s_load_dwordx2 s[24:25], s[18:19], 0xc8
	s_load_dwordx4 s[12:15], s[18:19], 0xe0
	s_waitcnt vmcnt(0)
	v_mov_b32_e32 v8, v128
	v_mov_b32_e32 v9, v129
	v_mov_b32_e32 v10, v130
	v_mov_b32_e32 v11, v131
	v_mov_b32_e32 v76, v132
	v_mov_b32_e32 v77, v133
	v_mov_b32_e32 v78, v134
	v_mov_b32_e32 v79, v135
	v_mov_b32_e32 v32, v136
	v_mov_b32_e32 v33, v137
	v_mov_b32_e32 v34, v138
	v_mov_b32_e32 v35, v139
	v_mov_b32_e32 v36, v140
	v_mov_b32_e32 v37, v141
	v_mov_b32_e32 v38, v142
	v_mov_b32_e32 v39, v143
	v_mov_b32_e32 v24, v144
	v_mov_b32_e32 v25, v145
	v_mov_b32_e32 v26, v146
	v_mov_b32_e32 v27, v147
	v_mov_b32_e32 v80, v148
	v_mov_b32_e32 v81, v149
	v_mov_b32_e32 v82, v150
	v_mov_b32_e32 v83, v151
	v_mov_b32_e32 v28, v152
	v_mov_b32_e32 v29, v153
	v_mov_b32_e32 v30, v154
	v_mov_b32_e32 v31, v155
	v_mov_b32_e32 v72, v158
	v_mov_b32_e32 v73, v159
	v_mov_b32_e32 v74, v160
	v_mov_b32_e32 v75, v161
	v_mov_b32_e32 v0, v162
	v_mov_b32_e32 v1, v163
	v_mov_b32_e32 v2, v164
	v_mov_b32_e32 v3, v165
	v_lshlrev_b32_e32 v110, 16, v80
	v_and_b32_e32 v111, 0xffff0000, v80
	v_lshlrev_b32_e32 v112, 16, v81
	v_and_b32_e32 v113, 0xffff0000, v81
	s_waitcnt lgkmcnt(0)
	global_load_dwordx4 v[84:87], v156, s[24:25]
	global_load_dwordx4 v[94:97], v156, s[12:13]
	s_load_dwordx2 s[20:21], s[18:19], 0xf0
	v_lshlrev_b32_e32 v114, 16, v82
	v_and_b32_e32 v115, 0xffff0000, v82
	v_lshlrev_b32_e32 v116, 16, v83
	v_and_b32_e32 v117, 0xffff0000, v83
	global_load_dwordx4 v[80:83], v156, s[14:15]
	s_waitcnt lgkmcnt(0)
	global_load_dwordx4 v[98:101], v156, s[20:21]
	v_lshlrev_b32_e32 v105, 16, v72
	v_and_b32_e32 v118, 0xffff0000, v72
	v_lshlrev_b32_e32 v119, 16, v73
	v_and_b32_e32 v120, 0xffff0000, v73
	v_lshlrev_b32_e32 v121, 16, v74
	v_and_b32_e32 v122, 0xffff0000, v74
	v_lshlrev_b32_e32 v123, 16, v75
	v_and_b32_e32 v124, 0xffff0000, v75
	global_load_dwordx4 v[72:75], v156, s[24:25] offset:16
	v_and_b32_e32 v89, 0xffff0000, v76
	v_lshlrev_b32_e32 v90, 16, v77
	v_and_b32_e32 v91, 0xffff0000, v77
	v_lshlrev_b32_e32 v104, 16, v76
	v_cndmask_b32_e64 v104, v104, v60, s[2:3]
	v_cndmask_b32_e64 v89, v89, v61, s[2:3]
	v_cndmask_b32_e64 v90, v90, v62, s[2:3]
	v_cndmask_b32_e64 v91, v91, v63, s[2:3]
	global_load_dwordx4 v[60:63], v156, s[14:15] offset:16
	v_lshlrev_b32_e32 v92, 16, v78
	v_and_b32_e32 v93, 0xffff0000, v78
	v_lshlrev_b32_e32 v102, 16, v79
	v_and_b32_e32 v103, 0xffff0000, v79
	v_and_b32_e32 v77, 0xffff0000, v36
	v_lshlrev_b32_e32 v76, 16, v36
	v_and_b32_e32 v36, 0xffff0000, v32
	v_lshlrev_b32_e32 v32, 16, v32
	v_and_b32_e32 v79, 0xffff0000, v37
	v_lshlrev_b32_e32 v78, 16, v37
	v_and_b32_e32 v37, 0xffff0000, v33
	v_lshlrev_b32_e32 v125, 16, v33
	v_cndmask_b32_e64 v92, v92, v64, s[2:3]
	v_cndmask_b32_e64 v93, v93, v65, s[2:3]
	v_cndmask_b32_e64 v102, v102, v66, s[2:3]
	v_cndmask_b32_e64 v103, v103, v67, s[2:3]
	v_cndmask_b32_e64 v33, v36, v69, s[2:3]
	v_cndmask_b32_e64 v32, v32, v68, s[2:3]
	v_cndmask_b32_e64 v37, v37, v71, s[2:3]
	v_cndmask_b32_e64 v36, v125, v70, s[2:3]
	global_load_dwordx4 v[64:67], v156, s[20:21] offset:16
	global_load_dwordx4 v[68:71], v156, s[12:13] offset:16
	v_pk_add_f32 v[32:33], v[32:33], v[76:77] neg_lo:[0,1] neg_hi:[0,1]
	v_sub_f32_e32 v102, v102, v116
	v_sub_f32_e32 v103, v103, v117
	v_pk_fma_f32 v[32:33], v[48:49], v[32:33], v[76:77]
	v_fmac_f32_e32 v116, v54, v102
	v_fmac_f32_e32 v117, v55, v103
	v_sub_f32_e32 v92, v92, v114
	v_sub_f32_e32 v93, v93, v115
	v_fmac_f32_e32 v114, v52, v92
	v_fmac_f32_e32 v115, v53, v93
	v_sub_f32_e32 v90, v90, v112
	v_sub_f32_e32 v91, v91, v113
	v_fmac_f32_e32 v112, v58, v90
	v_fmac_f32_e32 v113, v59, v91
	v_sub_f32_e32 v104, v104, v110
	v_sub_f32_e32 v89, v89, v111
	v_fmac_f32_e32 v110, v56, v104
	v_fmac_f32_e32 v111, v57, v89
	s_waitcnt vmcnt(7)
	v_add_f32_e32 v48, v84, v105
	v_add_f32_e32 v49, v85, v118
	v_mul_f32_e32 v54, 0xbfb8aa3b, v48
	v_mul_f32_e32 v55, 0xbfb8aa3b, v49
	v_exp_f32_e32 v54, v54
	v_exp_f32_e32 v55, v55
	v_add_f32_e32 v52, v86, v119
	v_add_f32_e32 v53, v87, v120
	v_mul_f32_e32 v52, 0xbfb8aa3b, v52
	v_mul_f32_e32 v53, 0xbfb8aa3b, v53
	v_exp_f32_e32 v52, v52
	v_exp_f32_e32 v53, v53
	v_add_f32_e32 v54, 1.0, v54
	v_add_f32_e32 v55, 1.0, v55
	v_rcp_f32_e32 v92, v54
	v_rcp_f32_e32 v93, v55
	v_add_f32_e32 v52, 1.0, v52
	v_add_f32_e32 v53, 1.0, v53
	s_waitcnt vmcnt(6)
	v_pk_mul_f32 v[90:91], v[32:33], v[94:95]
	v_rcp_f32_e32 v94, v52
	v_rcp_f32_e32 v95, v53
	v_pk_add_f32 v[52:53], v[92:93], -1.0 op_sel_hi:[1,0]
	v_pk_mul_f32 v[48:49], v[90:91], v[90:91]
	s_waitcnt vmcnt(5)
	v_pk_fma_f32 v[52:53], v[80:81], v[52:53], 1.0 op_sel_hi:[1,1,0]
	v_lshlrev_b32_e32 v118, 6, v109
	v_pk_mul_f32 v[80:81], v[32:33], v[52:53]
	s_nop 0
	v_mul_f32_e32 v32, v110, v80
	v_mul_f32_e32 v33, v111, v81
	s_waitcnt vmcnt(4)
	v_fma_f32 v52, v98, v32, 0
	v_fmac_f32_e32 v52, v99, v33
	v_pk_add_f32 v[32:33], v[36:37], v[78:79] neg_lo:[0,1] neg_hi:[0,1]
	v_pk_add_f32 v[36:37], v[94:95], -1.0 op_sel_hi:[1,0]
	v_pk_fma_f32 v[32:33], v[50:51], v[32:33], v[78:79]
	v_pk_fma_f32 v[36:37], v[82:83], v[36:37], 1.0 op_sel_hi:[1,1,0]
	s_waitcnt vmcnt(3)
	v_add_f32_e32 v50, v73, v122
	v_pk_mul_f32 v[82:83], v[32:33], v[36:37]
	v_add_f32_e32 v37, v72, v121
	v_mul_f32_e32 v37, 0xbfb8aa3b, v37
	v_exp_f32_e32 v37, v37
	v_mul_f32_e32 v50, 0xbfb8aa3b, v50
	v_exp_f32_e32 v50, v50
	v_mul_f32_e32 v36, v112, v82
	v_fmac_f32_e32 v52, v100, v36
	v_mul_f32_e32 v36, v113, v83
	v_fmac_f32_e32 v52, v101, v36
	v_add_f32_e32 v36, 1.0, v37
	v_rcp_f32_e32 v98, v36
	v_add_f32_e32 v36, 1.0, v50
	v_rcp_f32_e32 v99, v36
	v_and_b32_e32 v37, 0xffff0000, v38
	v_lshlrev_b32_e32 v36, 16, v38
	v_and_b32_e32 v38, 0xffff0000, v34
	v_lshlrev_b32_e32 v34, 16, v34
	v_cndmask_b32_e64 v45, v38, v45, s[2:3]
	v_cndmask_b32_e64 v44, v34, v44, s[2:3]
	v_pk_add_f32 v[44:45], v[44:45], v[36:37] neg_lo:[0,1] neg_hi:[0,1]
	v_add_f32_e32 v38, v74, v123
	v_pk_fma_f32 v[36:37], v[40:41], v[44:45], v[36:37]
	v_pk_add_f32 v[40:41], v[98:99], -1.0 op_sel_hi:[1,0]
	v_mul_f32_e32 v38, 0xbfb8aa3b, v38
	s_waitcnt vmcnt(2)
	v_pk_fma_f32 v[40:41], v[60:61], v[40:41], 1.0 op_sel_hi:[1,1,0]
	v_exp_f32_e32 v38, v38
	v_pk_mul_f32 v[84:85], v[36:37], v[40:41]
	v_add_f32_e32 v40, v75, v124
	v_mul_f32_e32 v40, 0xbfb8aa3b, v40
	v_exp_f32_e32 v40, v40
	v_mul_f32_e32 v34, v114, v84
	s_waitcnt vmcnt(1)
	v_fmac_f32_e32 v52, v64, v34
	v_mul_f32_e32 v34, v115, v85
	v_fmac_f32_e32 v52, v65, v34
	v_add_f32_e32 v34, 1.0, v38
	v_rcp_f32_e32 v102, v34
	v_add_f32_e32 v34, 1.0, v40
	v_rcp_f32_e32 v103, v34
	v_and_b32_e32 v34, 0xffff0000, v35
	v_lshlrev_b32_e32 v38, 16, v35
	v_and_b32_e32 v41, 0xffff0000, v39
	v_lshlrev_b32_e32 v40, 16, v39
	v_cndmask_b32_e64 v35, v34, v47, s[2:3]
	v_cndmask_b32_e64 v34, v38, v46, s[2:3]
	v_pk_add_f32 v[34:35], v[34:35], v[40:41] neg_lo:[0,1] neg_hi:[0,1]
	v_pk_add_f32 v[38:39], v[102:103], -1.0 op_sel_hi:[1,0]
	v_pk_fma_f32 v[34:35], v[42:43], v[34:35], v[40:41]
	v_pk_fma_f32 v[38:39], v[62:63], v[38:39], 1.0 op_sel_hi:[1,1,0]
	v_pk_mul_f32 v[96:97], v[32:33], v[96:97]
	v_pk_mul_f32 v[86:87], v[34:35], v[38:39]
	v_pk_mul_f32 v[32:33], v[96:97], v[96:97]
	v_mul_f32_e32 v38, v116, v86
	v_fmac_f32_e32 v52, v66, v38
	v_add_f32_e32 v38, v48, v49
	s_waitcnt vmcnt(0)
	v_pk_mul_f32 v[100:101], v[36:37], v[68:69]
	v_add_f32_e32 v32, v32, v38
	v_pk_mul_f32 v[36:37], v[100:101], v[100:101]
	v_add_f32_e32 v32, v33, v32
	v_pk_mul_f32 v[104:105], v[34:35], v[70:71]
	v_add_f32_e32 v32, v32, v36
	v_pk_mul_f32 v[34:35], v[104:105], v[104:105]
	v_add_f32_e32 v32, v37, v32
	v_add_f32_e32 v32, v34, v32
	v_add_f32_e32 v32, v35, v32
	v_mul_f32_e32 v33, v117, v87
	v_fmac_f32_e32 v52, v67, v33
	v_add_f32_dpp v32, v32, v32 quad_perm:[1,0,3,2] row_mask:0xf bank_mask:0xf bound_ctrl:1
	s_nop 1
	v_add_f32_dpp v89, v32, v32 quad_perm:[2,3,0,1] row_mask:0xf bank_mask:0xf bound_ctrl:1
	v_add_f32_dpp v32, v52, v52 quad_perm:[1,0,3,2] row_mask:0xf bank_mask:0xf bound_ctrl:1
	s_nop 0
	v_mov_b32_dpp v119, v89 row_half_mirror row_mask:0xf bank_mask:0xf bound_ctrl:1
	v_add_f32_dpp v120, v32, v32 quad_perm:[2,3,0,1] row_mask:0xf bank_mask:0xf bound_ctrl:1
	s_nop 1
	v_mov_b32_dpp v121, v120 row_half_mirror row_mask:0xf bank_mask:0xf bound_ctrl:1
	s_and_saveexec_b64 s[12:13], s[4:5]
	s_xor_b64 s[4:5], exec, s[12:13]
	v_lshlrev_b32_e32 v118, 6, v109
	s_or_saveexec_b64 s[12:13], s[4:5]
	s_ashr_i32 s7, s6, 31
	v_mov_b32_e32 v55, 1.0
	v_mov_b32_e32 v63, 0
	v_lshlrev_b32_e32 v88, 2, v88
	v_mov_b32_e32 v62, 0
	v_mov_b32_e32 v61, 0
	v_mov_b32_e32 v60, 0
	v_mov_b32_e32 v67, 0
	v_mov_b32_e32 v66, 0
	v_mov_b32_e32 v65, 0
	v_mov_b32_e32 v64, 0
	v_mov_b32_e32 v59, 0
	v_mov_b32_e32 v58, 0
	v_mov_b32_e32 v57, 0
	v_mov_b32_e32 v56, 0
	v_mov_b32_e32 v75, 0
	v_mov_b32_e32 v74, 0
	v_mov_b32_e32 v73, 0
	v_mov_b32_e32 v72, 0
	v_mov_b32_e32 v54, 1.0
	v_mov_b32_e32 v53, 1.0
	v_mov_b32_e32 v52, 1.0
	v_mov_b32_e32 v48, 1.0
	v_mov_b32_e32 v49, 1.0
	v_mov_b32_e32 v50, 1.0
	v_mov_b32_e32 v51, 1.0
	v_mov_b32_e32 v70, 0
	v_mov_b32_e32 v71, 0
	v_mov_b32_e32 v68, 0
	v_mov_b32_e32 v69, 0
	v_mov_b32_e32 v78, 0
	v_mov_b32_e32 v79, 0
	v_mov_b32_e32 v76, 0
	v_mov_b32_e32 v77, 0
	v_mov_b32_e32 v34, 0
	v_mov_b32_e32 v35, 0
	v_mov_b32_e32 v32, 0
	v_mov_b32_e32 v33, 0
	v_mov_b32_e32 v42, 0
	v_mov_b32_e32 v43, 0
	v_mov_b32_e32 v40, 0
	v_mov_b32_e32 v41, 0
	v_mov_b32_e32 v38, 0
	v_mov_b32_e32 v39, 0
	v_mov_b32_e32 v36, 0
	v_mov_b32_e32 v37, 0
	v_mov_b32_e32 v46, 0
	v_mov_b32_e32 v47, 0
	v_mov_b32_e32 v44, 0
	v_mov_b32_e32 v45, 0
	s_xor_b64 exec, exec, s[12:13]
	s_cbranch_execz .LBB0_332
	s_load_dwordx2 s[4:5], s[18:19], 0xb8
	v_add_f32_e32 v32, v89, v119
	s_mov_b32 s1, 0xf800000
	v_mul_f32_e32 v33, 0x4f800000, v32
	v_cmp_gt_f32_e32 vcc, s1, v32
	s_waitcnt lgkmcnt(0)
	global_load_dwordx4 v[48:51], v156, s[4:5] offset:16
	global_load_dwordx4 v[52:55], v156, s[4:5]
	v_cndmask_b32_e32 v32, v32, v33, vcc
	v_sqrt_f32_e32 v33, v32
	v_and_b32_e32 v57, 0xffff0000, v11
	v_lshlrev_b32_e32 v66, 16, v11
	v_and_b32_e32 v67, 0xffff0000, v10
	v_add_u32_e32 v11, -1, v33
	v_add_u32_e32 v34, 1, v33
	v_fma_f32 v35, -v11, v33, v32
	v_fma_f32 v36, -v34, v33, v32
	v_cmp_ge_f32_e64 s[4:5], 0, v35
	v_lshlrev_b32_e32 v68, 16, v10
	v_and_b32_e32 v64, 0xffff0000, v31
	v_cndmask_b32_e64 v11, v33, v11, s[4:5]
	v_cmp_lt_f32_e64 s[4:5], 0, v36
	v_lshlrev_b32_e32 v65, 16, v31
	v_and_b32_e32 v60, 0xffff0000, v30
	v_cndmask_b32_e64 v11, v11, v34, s[4:5]
	v_mul_f32_e32 v33, 0x37800000, v11
	v_cndmask_b32_e32 v11, v11, v33, vcc
	v_cmp_class_f32_e32 vcc, v32, v196
	v_lshlrev_b32_e32 v61, 16, v30
	v_and_b32_e32 v31, 0xffff0000, v25
	v_cndmask_b32_e32 v11, v11, v32, vcc
	v_max_f32_e32 v11, 0x2b8cbccc, v11
	v_div_scale_f32 v32, s[4:5], v11, v11, 1.0
	v_rcp_f32_e32 v33, v32
	v_div_scale_f32 v10, vcc, 1.0, v11, 1.0
	v_lshlrev_b32_e32 v30, 16, v25
	v_fma_f32 v34, -v32, v33, 1.0
	v_fmac_f32_e32 v33, v34, v33
	v_mul_f32_e32 v34, v10, v33
	v_fma_f32 v35, -v32, v34, v10
	v_fmac_f32_e32 v34, v35, v33
	v_fma_f32 v10, -v32, v34, v10
	v_div_fmas_f32 v10, v10, v33, v34
	v_div_fixup_f32 v10, v10, v11, 1.0
	v_pk_mul_f32 v[32:33], v[104:105], v[10:11] op_sel_hi:[1,0]
	v_pk_mul_f32 v[40:41], v[100:101], v[10:11] op_sel_hi:[1,0]
	v_pk_mul_f32 v[42:43], v[96:97], v[10:11] op_sel_hi:[1,0]
	v_pk_mul_f32 v[10:11], v[90:91], v[10:11] op_sel_hi:[1,0]
	v_pk_mul_f32 v[38:39], v[102:103], v[32:33]
	v_pk_add_f32 v[34:35], v[32:33], 0 neg_lo:[1,1] neg_hi:[1,1]
	v_pk_mul_f32 v[36:37], v[98:99], v[40:41]
	v_pk_add_f32 v[32:33], v[40:41], 0 neg_lo:[1,1] neg_hi:[1,1]
	v_pk_mul_f32 v[44:45], v[92:93], v[10:11]
	v_pk_add_f32 v[40:41], v[10:11], 0 neg_lo:[1,1] neg_hi:[1,1]
	v_and_b32_e32 v25, 0xffff0000, v28
	v_lshlrev_b32_e32 v56, 16, v28
	v_and_b32_e32 v58, 0xffff0000, v29
	v_lshlrev_b32_e32 v59, 16, v29
	v_and_b32_e32 v29, 0xffff0000, v24
	v_lshlrev_b32_e32 v28, 16, v24
	v_add_f32_e32 v24, v120, v121
	v_and_b32_e32 v63, 0xffff0000, v27
	v_lshlrev_b32_e32 v62, 16, v27
	v_and_b32_e32 v27, 0xffff0000, v26
	v_lshlrev_b32_e32 v26, 16, v26
	v_lshlrev_b32_e32 v156, 8, v109
	v_mov_b32_e32 v89, v157
	v_pk_mul_f32 v[46:47], v[94:95], v[42:43]
	v_pk_add_f32 v[42:43], v[42:43], 0 neg_lo:[1,1] neg_hi:[1,1]
	v_mov_b32_e32 v75, v113
	v_mov_b32_e32 v74, v112
	v_mov_b32_e32 v73, v111
	v_mov_b32_e32 v72, v110
	v_mov_b32_e32 v70, v86
	v_mov_b32_e32 v71, v87
	v_mov_b32_e32 v69, v85
	v_mov_b32_e32 v78, v82
	v_mov_b32_e32 v79, v83
	v_mov_b32_e32 v76, v80
	v_mov_b32_e32 v77, v81
	s_waitcnt vmcnt(1)
	v_add_f32_e32 v10, v51, v57
	v_add_f32_e32 v11, v50, v66
	v_mul_f32_e32 v50, 0xbfb8aa3b, v10
	v_exp_f32_e32 v50, v50
	v_mul_f32_e32 v51, 0xbfb8aa3b, v11
	v_add_f32_e32 v49, v49, v67
	v_exp_f32_e32 v51, v51
	v_add_f32_e32 v50, 1.0, v50
	v_log_f32_e32 v50, v50
	v_mul_f32_e32 v57, 0xbfb8aa3b, v49
	v_cmp_gt_f32_e32 vcc, s95, v10
	v_exp_f32_e32 v57, v57
	v_mul_f32_e32 v50, 0x3f317218, v50
	v_cndmask_b32_e64 v10, v50, -v10, vcc
	v_sub_f32_e32 v10, -0.5, v10
	v_add_f32_e32 v48, v48, v68
	v_add_f32_e32 v51, 1.0, v51
	v_mul_f32_e32 v10, 0x3fb8aa3b, v10
	v_mul_f32_e32 v66, 0xbfb8aa3b, v48
	v_log_f32_e32 v51, v51
	v_exp_f32_e32 v10, v10
	v_add_f32_e32 v57, 1.0, v57
	v_exp_f32_e32 v66, v66
	v_log_f32_e32 v57, v57
	v_mul_f32_e32 v51, 0x3f317218, v51
	v_cmp_gt_f32_e32 vcc, s95, v11
	v_mul_f32_e32 v10, 0xbfb8aa3b, v10
	v_mul_f32_e32 v57, 0x3f317218, v57
	v_cndmask_b32_e64 v11, v51, -v11, vcc
	v_exp_f32_e32 v51, v10
	v_add_f32_e32 v10, 1.0, v66
	v_cmp_gt_f32_e32 vcc, s95, v49
	v_log_f32_e32 v10, v10
	v_sub_f32_e32 v11, -0.5, v11
	v_cndmask_b32_e64 v49, v57, -v49, vcc
	v_sub_f32_e32 v49, -0.5, v49
	v_mul_f32_e32 v11, 0x3fb8aa3b, v11
	v_mul_f32_e32 v49, 0x3fb8aa3b, v49
	v_exp_f32_e32 v11, v11
	v_exp_f32_e32 v49, v49
	v_mul_f32_e32 v10, 0x3f317218, v10
	v_cmp_gt_f32_e32 vcc, s95, v48
	v_mul_f32_e32 v11, 0xbfb8aa3b, v11
	v_exp_f32_e32 v50, v11
	v_cndmask_b32_e64 v10, v10, -v48, vcc
	v_sub_f32_e32 v10, -0.5, v10
	v_and_b32_e32 v48, 0xffff0000, v9
	v_mul_f32_e32 v10, 0x3fb8aa3b, v10
	s_waitcnt vmcnt(0)
	v_add_f32_e32 v55, v55, v48
	v_lshlrev_b32_e32 v9, 16, v9
	v_mul_f32_e32 v11, 0xbfb8aa3b, v49
	v_exp_f32_e32 v10, v10
	v_mul_f32_e32 v48, 0xbfb8aa3b, v55
	v_add_f32_e32 v9, v54, v9
	v_exp_f32_e32 v57, v48
	v_exp_f32_e32 v49, v11
	v_mul_f32_e32 v11, 0xbfb8aa3b, v9
	v_exp_f32_e32 v11, v11
	v_mul_f32_e32 v10, 0xbfb8aa3b, v10
	v_exp_f32_e32 v48, v10
	v_add_f32_e32 v10, 1.0, v57
	v_log_f32_e32 v10, v10
	v_add_f32_e32 v11, 1.0, v11
	v_log_f32_e32 v11, v11
	v_cmp_gt_f32_e32 vcc, s95, v55
	v_mul_f32_e32 v10, 0x3f317218, v10
	v_mov_b32_e32 v67, v117
	v_cndmask_b32_e64 v10, v10, -v55, vcc
	v_mul_f32_e32 v11, 0x3f317218, v11
	v_cmp_gt_f32_e32 vcc, s95, v9
	v_sub_f32_e32 v10, -0.5, v10
	v_mul_f32_e32 v10, 0x3fb8aa3b, v10
	v_cndmask_b32_e64 v9, v11, -v9, vcc
	v_and_b32_e32 v11, 0xffff0000, v8
	v_add_f32_e32 v11, v53, v11
	v_exp_f32_e32 v10, v10
	v_mul_f32_e32 v53, 0xbfb8aa3b, v11
	v_exp_f32_e32 v53, v53
	v_lshlrev_b32_e32 v8, 16, v8
	v_mul_f32_e32 v10, 0xbfb8aa3b, v10
	v_exp_f32_e32 v55, v10
	v_add_f32_e32 v10, 1.0, v53
	v_add_f32_e32 v8, v52, v8
	v_log_f32_e32 v10, v10
	v_mul_f32_e32 v52, 0xbfb8aa3b, v8
	v_exp_f32_e32 v52, v52
	v_cmp_gt_f32_e32 vcc, s95, v11
	v_mul_f32_e32 v10, 0x3f317218, v10
	v_sub_f32_e32 v9, -0.5, v9
	v_cndmask_b32_e64 v10, v10, -v11, vcc
	v_add_f32_e32 v11, 1.0, v52
	v_log_f32_e32 v11, v11
	v_cmp_gt_f32_e32 vcc, s95, v8
	v_mul_f32_e32 v9, 0x3fb8aa3b, v9
	v_sub_f32_e32 v10, -0.5, v10
	v_mul_f32_e32 v11, 0x3f317218, v11
	v_cndmask_b32_e64 v8, v11, -v8, vcc
	v_sub_f32_e32 v8, -0.5, v8
	v_exp_f32_e32 v9, v9
	v_mul_f32_e32 v10, 0x3fb8aa3b, v10
	v_mul_f32_e32 v8, 0x3fb8aa3b, v8
	v_exp_f32_e32 v10, v10
	v_exp_f32_e32 v8, v8
	v_mul_f32_e32 v9, 0xbfb8aa3b, v9
	v_exp_f32_e32 v54, v9
	v_mul_f32_e32 v9, 0xbfb8aa3b, v10
	v_mul_f32_e32 v8, 0xbfb8aa3b, v8
	v_exp_f32_e32 v53, v9
	v_exp_f32_e32 v52, v8
	v_cndmask_b32_e64 v9, v25, v21, s[2:3]
	v_cndmask_b32_e64 v8, v56, v20, s[2:3]
	v_pk_add_f32 v[8:9], v[8:9], v[28:29] neg_lo:[0,1] neg_hi:[0,1]
	v_mov_b32_e32 v66, v116
	v_pk_fma_f32 v[56:57], v[12:13], v[8:9], v[28:29]
	v_mov_b32_e32 v68, v84
	v_pk_mul_f32 v[8:9], v[56:57], v[24:25] op_sel_hi:[1,0]
	s_nop 0
	v_and_b32_sdwa v10, v9, v195 dst_sel:DWORD dst_unused:UNUSED_PAD src0_sel:WORD_1 src1_sel:DWORD
	v_and_b32_sdwa v11, v8, v195 dst_sel:DWORD dst_unused:UNUSED_PAD src0_sel:WORD_1 src1_sel:DWORD
	v_add3_u32 v9, v9, v10, s54
	v_add3_u32 v8, v8, v11, s54
	v_cndmask_b32_e64 v11, v58, v23, s[2:3]
	v_cndmask_b32_e64 v10, v59, v22, s[2:3]
	v_pk_add_f32 v[10:11], v[10:11], v[30:31] neg_lo:[0,1] neg_hi:[0,1]
	v_and_b32_e32 v9, 0xffff0000, v9
	v_pk_fma_f32 v[58:59], v[14:15], v[10:11], v[30:31]
	v_and_b32_e32 v8, 0xffff0000, v8
	v_pk_mul_f32 v[10:11], v[58:59], v[24:25] op_sel_hi:[1,0]
	v_or_b32_sdwa v9, v9, v0 dst_sel:DWORD dst_unused:UNUSED_PAD src0_sel:DWORD src1_sel:WORD_1
	v_or_b32_sdwa v8, v8, v0 dst_sel:DWORD dst_unused:UNUSED_PAD src0_sel:DWORD src1_sel:WORD_0
	v_and_b32_sdwa v0, v11, v195 dst_sel:DWORD dst_unused:UNUSED_PAD src0_sel:WORD_1 src1_sel:DWORD
	v_and_b32_sdwa v12, v10, v195 dst_sel:DWORD dst_unused:UNUSED_PAD src0_sel:WORD_1 src1_sel:DWORD
	v_add3_u32 v0, v11, v0, s54
	v_add3_u32 v10, v10, v12, s54
	v_and_b32_e32 v0, 0xffff0000, v0
	v_and_b32_e32 v10, 0xffff0000, v10
	v_or_b32_sdwa v11, v0, v1 dst_sel:DWORD dst_unused:UNUSED_PAD src0_sel:DWORD src1_sel:WORD_1
	v_or_b32_sdwa v10, v10, v1 dst_sel:DWORD dst_unused:UNUSED_PAD src0_sel:DWORD src1_sel:WORD_0
	v_cndmask_b32_e64 v1, v60, v17, s[2:3]
	v_cndmask_b32_e64 v0, v61, v16, s[2:3]
	v_pk_add_f32 v[0:1], v[0:1], v[26:27] neg_lo:[0,1] neg_hi:[0,1]
	s_nop 0
	v_pk_fma_f32 v[60:61], v[4:5], v[0:1], v[26:27]
	s_nop 0
	v_pk_mul_f32 v[0:1], v[60:61], v[24:25] op_sel_hi:[1,0]
	s_nop 0
	v_and_b32_sdwa v4, v1, v195 dst_sel:DWORD dst_unused:UNUSED_PAD src0_sel:WORD_1 src1_sel:DWORD
	v_and_b32_sdwa v5, v0, v195 dst_sel:DWORD dst_unused:UNUSED_PAD src0_sel:WORD_1 src1_sel:DWORD
	v_add3_u32 v1, v1, v4, s54
	v_add3_u32 v0, v0, v5, s54
	v_and_b32_e32 v1, 0xffff0000, v1
	v_and_b32_e32 v0, 0xffff0000, v0
	v_or_b32_sdwa v5, v1, v2 dst_sel:DWORD dst_unused:UNUSED_PAD src0_sel:DWORD src1_sel:WORD_1
	v_or_b32_sdwa v4, v0, v2 dst_sel:DWORD dst_unused:UNUSED_PAD src0_sel:DWORD src1_sel:WORD_0
	v_cndmask_b32_e64 v1, v64, v19, s[2:3]
	v_cndmask_b32_e64 v0, v65, v18, s[2:3]
	v_pk_add_f32 v[0:1], v[0:1], v[62:63] neg_lo:[0,1] neg_hi:[0,1]
	s_lshl_b64 s[2:3], s[6:7], 12
	v_pk_fma_f32 v[62:63], v[6:7], v[0:1], v[62:63]
	s_add_u32 s2, s16, s2
	v_pk_mul_f32 v[0:1], v[62:63], v[24:25] op_sel_hi:[1,0]
	s_addc_u32 s3, s17, s3
	v_and_b32_sdwa v2, v1, v195 dst_sel:DWORD dst_unused:UNUSED_PAD src0_sel:WORD_1 src1_sel:DWORD
	v_and_b32_sdwa v6, v0, v195 dst_sel:DWORD dst_unused:UNUSED_PAD src0_sel:WORD_1 src1_sel:DWORD
	v_add3_u32 v1, v1, v2, s54
	v_add3_u32 v0, v0, v6, s54
	v_and_b32_e32 v1, 0xffff0000, v1
	v_and_b32_e32 v0, 0xffff0000, v0
	v_or_b32_sdwa v7, v1, v3 dst_sel:DWORD dst_unused:UNUSED_PAD src0_sel:DWORD src1_sel:WORD_1
	v_or_b32_sdwa v6, v0, v3 dst_sel:DWORD dst_unused:UNUSED_PAD src0_sel:DWORD src1_sel:WORD_0
	v_lshl_add_u64 v[0:1], s[2:3], 0, v[156:157]
	v_lshl_add_u64 v[0:1], v[0:1], 0, v[88:89]
	s_mov_b64 s[2:3], 0x34800000
	v_lshl_add_u64 v[2:3], v[0:1], 0, s[2:3]
	v_add_co_u32_e32 v0, vcc, s96, v0
	v_mov_b32_e32 v65, v115
	s_nop 0
	v_addc_co_u32_e32 v1, vcc, 0, v1, vcc
	v_mov_b32_e32 v64, v114
	global_store_dwordx4 v[0:1], v[8:11], off
	global_store_dwordx4 v[2:3], v[4:7], off offset:16
.LBB0_332:
	s_or_b64 exec, exec, s[12:13]
	s_add_i32 s100, s8, s9
	s_cmpk_ge_i32 s100, 0x2400
	s_cbranch_scc1 .Lr1pf_skip
	v_mbcnt_lo_u32_b32 v166, -1, 0
	v_mbcnt_hi_u32_b32 v166, -1, v166
	v_add_u32_e32 v167, s61, v166
	v_lshrrev_b32_e32 v168, 7, v167
	v_add_u32_e32 v168, s100, v168
	s_load_dwordx2 s[100:101], s[58:59], 0x158
	v_lshlrev_b32_e32 v169, 4, v168
	v_and_b32_e32 v169, 0x7f0, v169
	v_ashrrev_i32_e32 v170, 10, v168
	v_lshl_or_b32 v170, v170, 11, v169
	v_lshrrev_b32_e32 v171, 7, v168
	v_add_u32_e32 v172, 0xffffe000, v168
	v_and_b32_e32 v172, -8, v172
	v_add_u32_e32 v172, 0x4000, v172
	v_cmp_lt_i32_e32 vcc, 0x1fff, v168
	v_cndmask_b32_e32 v170, v170, v172, vcc
	v_cndmask_b32_e64 v169, v169, 0, vcc
	v_cndmask_b32_e32 v171, v171, v168, vcc
	v_mov_b32_e32 v173, 16
	v_cndmask_b32_e64 v173, v173, 8, vcc
	v_bfe_u32 v174, v167, 6, 1
	v_bfe_u32 v175, v166, 3, 3
	v_lshl_or_b32 v174, v174, 3, v175
	v_cmp_gt_u32_e32 vcc, v173, v174
	v_cndmask_b32_e32 v174, 0, v174, vcc
	v_lshlrev_b32_e32 v171, 6, v171
	v_and_b32_e32 v171, 0x1c0, v171
	v_lshlrev_b32_e32 v175, 3, v167
	v_and_b32_e32 v175, 56, v175
	v_or_b32_e32 v171, v171, v175
	v_add_u32_e32 v170, v170, v174
	v_or_b32_e32 v169, v169, v174
	v_lshlrev_b32_e32 v176, 1, v171
	v_mov_b32_e32 v177, 0
	v_mov_b32_e32 v178, 0xc00
	s_waitcnt lgkmcnt(0)
	v_mov_b64_e32 v[180:181], s[100:101]
	v_mov_b64_e32 v[182:183], s[100:101]
	v_mad_i64_i32 v[180:181], vcc, v170, s83, v[180:181]
	v_mad_i64_i32 v[182:183], vcc, v170, v178, v[182:183]
	v_lshl_add_u64 v[180:181], v[180:181], 0, v[176:177]
	v_lshl_add_u64 v[182:183], v[182:183], 0, v[176:177]
	v_add_co_u32_e32 v180, vcc, 0x12f01000, v180
	v_addc_co_u32_e32 v181, vcc, 0, v181, vcc
	v_add_co_u32_e32 v182, vcc, 0x25600000, v182
	v_addc_co_u32_e32 v183, vcc, 0, v183, vcc
	v_cmp_eq_u32_e32 vcc, 0, v169
	v_cndmask_b32_e64 v185, -1, 0, vcc
	v_cndmask_b32_e64 v184, v205, 0, vcc
	v_lshl_add_u64 v[184:185], v[180:181], 0, v[184:185]
	global_load_dwordx4 v[128:131], v[182:183], off
	global_load_dwordx4 v[132:135], v[184:185], off
	global_load_dwordx4 v[136:139], v[184:185], off offset:1024
	global_load_dwordx4 v[140:143], v[180:181], off offset:1024
	global_load_dwordx4 v[144:147], v[180:181], off offset:2048
	global_load_dwordx4 v[148:151], v[180:181], off
	global_load_dwordx4 v[152:155], v[184:185], off offset:2048
	global_load_dwordx4 v[158:161], v[182:183], off offset:1024
	global_load_dwordx4 v[162:165], v[182:183], off offset:2048
.Lr1pf_skip:
	s_mul_i32 s0, s0, 0x8800
	s_add_i32 s16, s0, 0
	s_mul_i32 s1, s6, 0x4800
	s_mul_hi_i32 s0, s6, 0x4800
	s_add_u32 s1, s10, s1
	s_addc_u32 s0, s11, s0
	v_mul_u32_u24_e32 v0, 0x44, v109
	s_add_u32 s12, s1, 0x2a600000
	v_and_b32_e32 v16, 0x7f, v108
	v_lshlrev_b32_e32 v0, 2, v0
	s_addc_u32 s13, s0, 0
	v_add3_u32 v0, s16, v0, v88
	v_lshlrev_b32_e32 v1, 2, v118
	v_cmp_gt_u32_e32 vcc, 64, v16
	v_add3_u32 v1, s16, v1, v88
	ds_write_b128 v0, v[72:75]
	ds_write_b128 v1, v[52:55] offset:17408
	ds_write_b128 v0, v[76:79] offset:4352
	ds_write_b128 v0, v[40:43] offset:8704
	ds_write_b128 v0, v[44:47] offset:13056
	ds_write_b128 v1, v[56:59] offset:28160
	ds_write_b128 v0, v[64:67] offset:16
	ds_write_b128 v1, v[48:51] offset:17424
	ds_write_b128 v0, v[68:71] offset:4368
	ds_write_b128 v0, v[32:35] offset:8720
	ds_write_b128 v0, v[36:39] offset:13072
	ds_write_b128 v1, v[60:63] offset:28176
	s_waitcnt lgkmcnt(0)
	s_barrier
	s_and_saveexec_b64 s[2:3], vcc
	s_cbranch_execz .LBB0_334
	v_lshlrev_b32_e32 v156, 2, v16
	v_add_u32_e32 v4, s16, v156
	v_add_u32_e32 v0, 0x4200, v4
	ds_read2_b32 v[0:1], v0 offset0:60 offset1:128
	v_add_u32_e32 v5, 0x3000, v4
	v_add_u32_e32 v17, 0x1000, v4
	ds_read2_b32 v[2:3], v5 offset0:124 offset1:192
	v_add_u32_e32 v27, 0x2200, v4
	s_waitcnt lgkmcnt(1)
	v_div_scale_f32 v6, s[0:1], v1, v1, 1.0
	v_rcp_f32_e32 v7, v6
	v_div_scale_f32 v8, vcc, 1.0, v1, 1.0
	v_add_u32_e32 v28, 0x3400, v4
	v_fma_f32 v9, -v6, v7, 1.0
	v_fmac_f32_e32 v7, v9, v7
	v_mul_f32_e32 v9, v8, v7
	v_fma_f32 v10, -v6, v9, v8
	v_fmac_f32_e32 v9, v10, v7
	v_fma_f32 v6, -v6, v9, v8
	v_div_fmas_f32 v6, v6, v7, v9
	v_div_fixup_f32 v20, v6, v1, 1.0
	ds_read2_b32 v[6:7], v17 offset0:64 offset1:132
	ds_read2st64_b32 v[8:9], v4 offset0:69 offset1:70
	ds_read2_b32 v[10:11], v4 offset1:68
	ds_read2st64_b32 v[12:13], v4 offset0:71 offset1:72
	ds_read2st64_b32 v[14:15], v4 offset0:73 offset1:74
	ds_read2st64_b32 v[18:19], v4 offset0:75 offset1:76
	s_waitcnt lgkmcnt(4)
	v_mul_f32_e32 v8, v1, v8
	v_div_scale_f32 v21, s[0:1], v8, v8, 1.0
	v_rcp_f32_e32 v24, v21
	v_mul_f32_e32 v3, v20, v3
	v_mul_f32_e32 v6, v20, v6
	s_waitcnt lgkmcnt(3)
	v_mul_f32_e32 v10, v1, v10
	v_fma_f32 v20, -v21, v24, 1.0
	v_fmac_f32_e32 v24, v20, v24
	v_div_scale_f32 v20, vcc, 1.0, v8, 1.0
	v_mul_f32_e32 v25, v20, v24
	v_fma_f32 v22, -v21, v25, v20
	v_fmac_f32_e32 v25, v22, v24
	v_fma_f32 v26, -v21, v25, v20
	ds_read2_b32 v[20:21], v27 offset0:68 offset1:136
	ds_read2_b32 v[22:23], v28 offset0:4 offset1:72
	v_div_fmas_f32 v24, v26, v24, v25
	v_div_fixup_f32 v24, v24, v8, 1.0
	v_mul_f32_e32 v7, v24, v7
	s_waitcnt lgkmcnt(1)
	v_mul_f32_e32 v1, v1, v20
	s_waitcnt lgkmcnt(0)
	v_mul_f32_e32 v20, v24, v22
	v_mul_f32_e32 v22, v8, v9
	v_div_scale_f32 v9, s[0:1], v22, v22, 1.0
	v_rcp_f32_e32 v24, v9
	ds_write2_b32 v17, v6, v7 offset0:64 offset1:132
	v_mul_f32_e32 v6, v8, v11
	ds_write2_b32 v4, v10, v6 offset1:68
	v_fma_f32 v6, -v9, v24, 1.0
	v_fmac_f32_e32 v24, v6, v24
	v_div_scale_f32 v6, vcc, 1.0, v22, 1.0
	v_mul_f32_e32 v7, v6, v24
	v_fma_f32 v10, -v9, v7, v6
	v_fmac_f32_e32 v7, v10, v24
	v_fma_f32 v6, -v9, v7, v6
	v_div_fmas_f32 v6, v6, v24, v7
	v_div_fixup_f32 v10, v6, v22, 1.0
	v_mul_f32_e32 v6, v8, v21
	ds_write2_b32 v27, v1, v6 offset0:68 offset1:136
	v_add_u32_e32 v17, 0x1200, v4
	v_mul_f32_e32 v12, v22, v12
	ds_read2_b32 v[6:7], v17 offset0:72 offset1:140
	ds_read2_b32 v[8:9], v4 offset0:136 offset1:204
	v_div_scale_f32 v11, s[0:1], v12, v12, 1.0
	v_mul_f32_e32 v1, v10, v23
	v_rcp_f32_e32 v23, v11
	ds_write2_b32 v28, v20, v1 offset0:4 offset1:72
	s_waitcnt lgkmcnt(2)
	v_mul_f32_e32 v1, v10, v6
	s_waitcnt lgkmcnt(1)
	v_mul_f32_e32 v6, v22, v8
	v_fma_f32 v8, -v11, v23, 1.0
	v_fmac_f32_e32 v23, v8, v23
	v_div_scale_f32 v8, vcc, 1.0, v12, 1.0
	v_mul_f32_e32 v24, v8, v23
	v_fma_f32 v10, -v11, v24, v8
	v_fmac_f32_e32 v24, v10, v23
	v_add_u32_e32 v25, 0x2400, v4
	v_fma_f32 v8, -v11, v24, v8
	ds_read2_b32 v[10:11], v25 offset0:76 offset1:144
	ds_read2_b32 v[20:21], v28 offset0:140 offset1:208
	v_div_fmas_f32 v8, v8, v23, v24
	v_div_fixup_f32 v8, v8, v12, 1.0
	v_mul_f32_e32 v7, v8, v7
	s_waitcnt lgkmcnt(1)
	v_mul_f32_e32 v10, v22, v10
	v_mul_f32_e32 v22, v12, v13
	s_waitcnt lgkmcnt(0)
	v_mul_f32_e32 v20, v8, v20
	v_div_scale_f32 v8, s[0:1], v22, v22, 1.0
	v_rcp_f32_e32 v13, v8
	ds_write2_b32 v17, v1, v7 offset0:72 offset1:140
	v_mul_f32_e32 v1, v12, v9
	ds_write2_b32 v4, v6, v1 offset0:136 offset1:204
	v_fma_f32 v1, -v8, v13, 1.0
	v_fmac_f32_e32 v13, v1, v13
	v_div_scale_f32 v1, vcc, 1.0, v22, 1.0
	v_mul_f32_e32 v6, v1, v13
	v_fma_f32 v7, -v8, v6, v1
	v_fmac_f32_e32 v6, v7, v13
	v_fma_f32 v1, -v8, v6, v1
	v_div_fmas_f32 v1, v1, v13, v6
	v_div_fixup_f32 v1, v1, v22, 1.0
	v_mul_f32_e32 v6, v12, v11
	ds_write2_b32 v25, v10, v6 offset0:76 offset1:144
	v_mul_f32_e32 v10, v1, v21
	v_add_u32_e32 v17, 0x1400, v4
	v_add_u32_e32 v21, 0x400, v4
	v_mul_f32_e32 v14, v22, v14
	ds_read2_b32 v[6:7], v17 offset0:80 offset1:148
	ds_read2_b32 v[8:9], v21 offset0:16 offset1:84
	v_div_scale_f32 v11, s[0:1], v14, v14, 1.0
	v_rcp_f32_e32 v23, v11
	s_waitcnt lgkmcnt(1)
	v_mul_f32_e32 v1, v1, v6
	s_waitcnt lgkmcnt(0)
	v_mul_f32_e32 v6, v22, v8
	ds_write2_b32 v28, v20, v10 offset0:140 offset1:208
	v_fma_f32 v8, -v11, v23, 1.0
	v_fmac_f32_e32 v23, v8, v23
	v_div_scale_f32 v8, vcc, 1.0, v14, 1.0
	v_mul_f32_e32 v20, v8, v23
	v_add_u32_e32 v25, 0x3800, v4
	v_fma_f32 v10, -v11, v20, v8
	ds_read2_b32 v[12:13], v25 offset0:20 offset1:88
	v_fmac_f32_e32 v20, v10, v23
	v_fma_f32 v8, -v11, v20, v8
	v_div_fmas_f32 v8, v8, v23, v20
	v_div_fixup_f32 v8, v8, v14, 1.0
	v_mul_f32_e32 v15, v14, v15
	s_waitcnt lgkmcnt(0)
	v_mul_f32_e32 v12, v8, v12
	v_mul_f32_e32 v7, v8, v7
	v_div_scale_f32 v8, s[0:1], v15, v15, 1.0
	v_rcp_f32_e32 v20, v8
	ds_write2_b32 v17, v1, v7 offset0:80 offset1:148
	v_mul_f32_e32 v1, v14, v9
	v_add_u32_e32 v24, 0x2600, v4
	ds_write2_b32 v21, v6, v1 offset0:16 offset1:84
	v_fma_f32 v1, -v8, v20, 1.0
	ds_read2_b32 v[10:11], v24 offset0:84 offset1:152
	v_fmac_f32_e32 v20, v1, v20
	v_div_scale_f32 v1, vcc, 1.0, v15, 1.0
	v_mul_f32_e32 v6, v1, v20
	v_fma_f32 v7, -v8, v6, v1
	v_fmac_f32_e32 v6, v7, v20
	v_fma_f32 v1, -v8, v6, v1
	s_waitcnt lgkmcnt(0)
	v_mul_f32_e32 v10, v22, v10
	v_div_fmas_f32 v1, v1, v20, v6
	v_mul_f32_e32 v6, v14, v11
	ds_write2_b32 v24, v10, v6 offset0:84 offset1:152
	v_add_u32_e32 v14, 0x1600, v4
	v_mul_f32_e32 v17, v15, v18
	ds_read2_b32 v[6:7], v14 offset0:88 offset1:156
	ds_read2_b32 v[8:9], v21 offset0:152 offset1:220
	v_div_scale_f32 v11, s[0:1], v17, v17, 1.0
	v_rcp_f32_e32 v18, v11
	v_div_fixup_f32 v1, v1, v15, 1.0
	v_mul_f32_e32 v10, v1, v13
	s_waitcnt lgkmcnt(1)
	v_mul_f32_e32 v1, v1, v6
	s_waitcnt lgkmcnt(0)
	v_mul_f32_e32 v6, v15, v8
	v_fma_f32 v8, -v11, v18, 1.0
	v_fmac_f32_e32 v18, v8, v18
	v_div_scale_f32 v8, vcc, 1.0, v17, 1.0
	v_mul_f32_e32 v20, v8, v18
	ds_write2_b32 v25, v12, v10 offset0:20 offset1:88
	v_fma_f32 v10, -v11, v20, v8
	v_fmac_f32_e32 v20, v10, v18
	v_add_u32_e32 v22, 0x2800, v4
	v_fma_f32 v8, -v11, v20, v8
	ds_read2_b32 v[10:11], v22 offset0:92 offset1:160
	ds_read2_b32 v[12:13], v25 offset0:156 offset1:224
	v_div_fmas_f32 v8, v8, v18, v20
	v_div_fixup_f32 v8, v8, v17, 1.0
	v_mul_f32_e32 v23, v17, v19
	v_mul_f32_e32 v7, v8, v7
	s_waitcnt lgkmcnt(0)
	v_mul_f32_e32 v18, v8, v12
	v_div_scale_f32 v8, s[0:1], v23, v23, 1.0
	v_rcp_f32_e32 v12, v8
	ds_write2_b32 v14, v1, v7 offset0:88 offset1:156
	v_mul_f32_e32 v1, v17, v9
	ds_write2_b32 v21, v6, v1 offset0:152 offset1:220
	v_fma_f32 v1, -v8, v12, 1.0
	v_fmac_f32_e32 v12, v1, v12
	v_div_scale_f32 v1, vcc, 1.0, v23, 1.0
	v_mul_f32_e32 v6, v1, v12
	v_fma_f32 v7, -v8, v6, v1
	v_fmac_f32_e32 v6, v7, v12
	v_fma_f32 v1, -v8, v6, v1
	v_mul_f32_e32 v10, v15, v10
	v_div_fmas_f32 v1, v1, v12, v6
	v_mul_f32_e32 v6, v17, v11
	v_div_fixup_f32 v1, v1, v23, 1.0
	ds_write2_b32 v22, v10, v6 offset0:92 offset1:160
	v_add_u32_e32 v22, 0x1800, v4
	v_mul_f32_e32 v17, v1, v13
	ds_read2_b32 v[6:7], v22 offset0:96 offset1:164
	v_add_u32_e32 v24, 0x800, v4
	ds_read2st64_b32 v[8:9], v4 offset0:77 offset1:78
	ds_read2_b32 v[10:11], v24 offset0:32 offset1:100
	ds_read2st64_b32 v[12:13], v4 offset0:79 offset1:80
	ds_read2st64_b32 v[14:15], v4 offset0:81 offset1:82
	ds_read_b32 v26, v4 offset:21248
	s_waitcnt lgkmcnt(4)
	v_mul_f32_e32 v8, v23, v8
	v_div_scale_f32 v19, s[0:1], v8, v8, 1.0
	v_rcp_f32_e32 v27, v19
	v_mul_f32_e32 v1, v1, v6
	s_waitcnt lgkmcnt(3)
	v_mul_f32_e32 v6, v23, v10
	ds_write2_b32 v25, v18, v17 offset0:156 offset1:224
	v_fma_f32 v10, -v19, v27, 1.0
	v_fmac_f32_e32 v27, v10, v27
	v_div_scale_f32 v10, vcc, 1.0, v8, 1.0
	v_mul_f32_e32 v17, v10, v27
	v_fma_f32 v18, -v19, v17, v10
	v_fmac_f32_e32 v17, v18, v27
	v_add_u32_e32 v25, 0x2a00, v4
	v_add_u32_e32 v28, 0x3c00, v4
	v_fma_f32 v10, -v19, v17, v10
	ds_read2_b32 v[18:19], v25 offset0:100 offset1:168
	ds_read2_b32 v[20:21], v28 offset0:36 offset1:104
	v_div_fmas_f32 v10, v10, v27, v17
	v_div_fixup_f32 v10, v10, v8, 1.0
	v_mul_f32_e32 v7, v10, v7
	s_waitcnt lgkmcnt(1)
	v_mul_f32_e32 v17, v23, v18
	s_waitcnt lgkmcnt(0)
	v_mul_f32_e32 v18, v10, v20
	v_mul_f32_e32 v20, v8, v9
	v_div_scale_f32 v9, s[0:1], v20, v20, 1.0
	v_rcp_f32_e32 v10, v9
	ds_write2_b32 v22, v1, v7 offset0:96 offset1:164
	v_mul_f32_e32 v1, v8, v11
	ds_write2_b32 v24, v6, v1 offset0:32 offset1:100
	v_fma_f32 v1, -v9, v10, 1.0
	v_fmac_f32_e32 v10, v1, v10
	v_div_scale_f32 v1, vcc, 1.0, v20, 1.0
	v_mul_f32_e32 v6, v1, v10
	v_fma_f32 v7, -v9, v6, v1
	v_fmac_f32_e32 v6, v7, v10
	v_fma_f32 v1, -v9, v6, v1
	v_div_fmas_f32 v1, v1, v10, v6
	v_mul_f32_e32 v6, v8, v19
	ds_write2_b32 v25, v17, v6 offset0:100 offset1:168
	v_add_u32_e32 v17, 0x1a00, v4
	v_mul_f32_e32 v12, v20, v12
	v_div_fixup_f32 v1, v1, v20, 1.0
	ds_read2_b32 v[6:7], v17 offset0:104 offset1:172
	ds_read2_b32 v[8:9], v24 offset0:168 offset1:236
	v_div_scale_f32 v11, s[0:1], v12, v12, 1.0
	v_mul_f32_e32 v10, v1, v21
	v_rcp_f32_e32 v21, v11
	s_waitcnt lgkmcnt(1)
	v_mul_f32_e32 v1, v1, v6
	s_waitcnt lgkmcnt(0)
	v_mul_f32_e32 v6, v20, v8
	ds_write2_b32 v28, v18, v10 offset0:36 offset1:104
	v_fma_f32 v8, -v11, v21, 1.0
	v_fmac_f32_e32 v21, v8, v21
	v_div_scale_f32 v8, vcc, 1.0, v12, 1.0
	v_mul_f32_e32 v22, v8, v21
	v_fma_f32 v10, -v11, v22, v8
	v_fmac_f32_e32 v22, v10, v21
	v_add_u32_e32 v23, 0x2c00, v4
	v_fma_f32 v8, -v11, v22, v8
	ds_read2_b32 v[10:11], v23 offset0:108 offset1:176
	ds_read2_b32 v[18:19], v28 offset0:172 offset1:240
	v_div_fmas_f32 v8, v8, v21, v22
	v_div_fixup_f32 v8, v8, v12, 1.0
	v_mul_f32_e32 v7, v8, v7
	s_waitcnt lgkmcnt(1)
	v_mul_f32_e32 v10, v20, v10
	v_mul_f32_e32 v20, v12, v13
	s_waitcnt lgkmcnt(0)
	v_mul_f32_e32 v18, v8, v18
	v_div_scale_f32 v8, s[0:1], v20, v20, 1.0
	v_rcp_f32_e32 v13, v8
	ds_write2_b32 v17, v1, v7 offset0:104 offset1:172
	v_mul_f32_e32 v1, v12, v9
	ds_write2_b32 v24, v6, v1 offset0:168 offset1:236
	v_fma_f32 v1, -v8, v13, 1.0
	v_fmac_f32_e32 v13, v1, v13
	v_div_scale_f32 v1, vcc, 1.0, v20, 1.0
	v_mul_f32_e32 v6, v1, v13
	v_fma_f32 v7, -v8, v6, v1
	v_fmac_f32_e32 v6, v7, v13
	v_fma_f32 v1, -v8, v6, v1
	v_div_fmas_f32 v1, v1, v13, v6
	v_div_fixup_f32 v1, v1, v20, 1.0
	v_mul_f32_e32 v6, v12, v11
	ds_write2_b32 v23, v10, v6 offset0:108 offset1:176
	v_mul_f32_e32 v10, v1, v19
	v_add_u32_e32 v17, 0x1c00, v4
	v_add_u32_e32 v19, 0xc00, v4
	v_mul_f32_e32 v14, v20, v14
	ds_read2_b32 v[6:7], v17 offset0:112 offset1:180
	ds_read2_b32 v[8:9], v19 offset0:48 offset1:116
	v_div_scale_f32 v11, s[0:1], v14, v14, 1.0
	v_rcp_f32_e32 v21, v11
	s_waitcnt lgkmcnt(1)
	v_mul_f32_e32 v1, v1, v6
	s_waitcnt lgkmcnt(0)
	v_mul_f32_e32 v6, v20, v8
	ds_write2_b32 v28, v18, v10 offset0:172 offset1:240
	v_fma_f32 v8, -v11, v21, 1.0
	v_fmac_f32_e32 v21, v8, v21
	v_div_scale_f32 v8, vcc, 1.0, v14, 1.0
	v_mul_f32_e32 v18, v8, v21
	v_add_u32_e32 v23, 0x4000, v4
	v_fma_f32 v10, -v11, v18, v8
	ds_read2_b32 v[12:13], v23 offset0:52 offset1:120
	v_fmac_f32_e32 v18, v10, v21
	v_fma_f32 v8, -v11, v18, v8
	v_div_fmas_f32 v8, v8, v21, v18
	v_div_fixup_f32 v8, v8, v14, 1.0
	v_mul_f32_e32 v15, v14, v15
	s_waitcnt lgkmcnt(0)
	v_mul_f32_e32 v12, v8, v12
	v_mul_f32_e32 v7, v8, v7
	v_div_scale_f32 v8, s[0:1], v15, v15, 1.0
	v_rcp_f32_e32 v18, v8
	ds_write2_b32 v17, v1, v7 offset0:112 offset1:180
	v_mul_f32_e32 v1, v14, v9
	ds_write2_b32 v19, v6, v1 offset0:48 offset1:116
	v_fma_f32 v1, -v8, v18, 1.0
	v_add_u32_e32 v22, 0x2e00, v4
	v_fmac_f32_e32 v18, v1, v18
	v_div_scale_f32 v1, vcc, 1.0, v15, 1.0
	ds_read2_b32 v[10:11], v22 offset0:116 offset1:184
	v_mul_f32_e32 v6, v1, v18
	v_fma_f32 v7, -v8, v6, v1
	v_fmac_f32_e32 v6, v7, v18
	v_fma_f32 v1, -v8, v6, v1
	v_div_fmas_f32 v1, v1, v18, v6
	s_waitcnt lgkmcnt(0)
	v_mul_f32_e32 v10, v20, v10
	v_div_fixup_f32 v1, v1, v15, 1.0
	v_mul_f32_e32 v6, v14, v11
	ds_write2_b32 v22, v10, v6 offset0:116 offset1:184
	v_mul_f32_e32 v10, v1, v13
	v_add_u32_e32 v11, 0x1e00, v4
	v_mul_f32_e32 v13, v15, v26
	ds_read2_b32 v[6:7], v11 offset0:120 offset1:188
	ds_read2_b32 v[8:9], v19 offset0:184 offset1:252
	v_div_scale_f32 v14, s[0:1], v13, v13, 1.0
	v_rcp_f32_e32 v17, v14
	s_waitcnt lgkmcnt(1)
	v_mul_f32_e32 v1, v1, v6
	s_waitcnt lgkmcnt(0)
	v_mul_f32_e32 v6, v15, v8
	ds_write2_b32 v23, v12, v10 offset0:52 offset1:120
	v_fma_f32 v8, -v14, v17, 1.0
	v_fmac_f32_e32 v17, v8, v17
	v_div_scale_f32 v8, vcc, 1.0, v13, 1.0
	v_mul_f32_e32 v10, v8, v17
	v_fma_f32 v12, -v14, v10, v8
	v_fmac_f32_e32 v10, v12, v17
	v_fma_f32 v8, -v14, v10, v8
	v_div_fmas_f32 v8, v8, v17, v10
	v_div_fixup_f32 v8, v8, v13, 1.0
	v_mul_f32_e32 v0, v8, v0
	ds_write_b32 v4, v0 offset:17136
	v_mul_f32_e32 v0, v8, v7
	v_mul_f32_e32 v2, v15, v2
	ds_write2_b32 v11, v1, v0 offset0:120 offset1:188
	v_mul_f32_e32 v0, v13, v9
	ds_write2_b32 v5, v2, v3 offset0:124 offset1:192
	ds_write2_b32 v19, v6, v0 offset0:184 offset1:252
	ds_write_b32 v4, v13 offset:27904
	v_lshl_add_u64 v[0:1], s[12:13], 0, v[156:157]
	v_add_co_u32_e32 v0, vcc, 0x4000, v0
	s_nop 1
	v_addc_co_u32_e32 v1, vcc, 0, v1, vcc
	global_store_dword v[0:1], v13, off offset:1408
